# MLA-up: activation tile loads issued together, row inverse-rms via ds_read_b128 (same fma order), shared rotary-key loop loads issued together
# baseline (speedup 1.0000x reference)
; DI void phase_mla_up(const Params& p, int layer, char* lds) {
;     ...
;       for (int c = tid; c < 128 * CPR; c += NTHR) { int row = c / CPR, ch = c % CPR;
;         *(u32x4*)(As + row * STR + ch * 16) = *(const u32x4*)(H + (size_t)(m0 + row) * DIN + acol + ch * 8); }
.LBB0_171:
	v_sub_u32_e32 v12, 0, v8
	v_max_i32_e32 v12, v8, v12
	v_mul_hi_u32 v13, v12, v6
	v_mul_lo_u32 v14, v13, s29
	v_sub_u32_e32 v12, v12, v14
	v_add_u32_e32 v15, 1, v13
	v_cmp_le_u32_e32 vcc, s29, v12
	v_subrev_u32_e32 v14, s29, v12
	v_ashrrev_i32_e32 v9, 31, v8
	v_cndmask_b32_e32 v13, v13, v15, vcc
	v_cndmask_b32_e32 v12, v12, v14, vcc
	v_add_u32_e32 v14, 1, v13
	v_cmp_le_u32_e32 vcc, s29, v12
	v_mov_b64_e32 v[10:11], s[24:25]
	v_add_u32_e32 v8, 0x200, v8
	v_cndmask_b32_e32 v12, v13, v14, vcc
	v_xor_b32_e32 v14, v12, v9
	v_sub_u32_e32 v12, v14, v9
	v_add_u32_e32 v15, s63, v12
	v_mad_u64_u32 v[12:13], s[54:55], s53, v12, v[4:5]
	v_mad_i64_i32 v[10:11], s[54:55], v15, s64, v[10:11]
	v_ashrrev_i32_e32 v13, 31, v12
	v_lshl_add_u64 v[10:11], v[12:13], 1, v[10:11]
	global_load_dwordx4 v[116:119], v[10:11], off
	v_lshlrev_b32_e32 v9, 4, v9
	v_lshlrev_b32_e32 v14, 4, v14
	v_sub_u32_e32 v9, v14, v9
	v_add_u32_e32 v4, 0x1000, v4
	v_add_u32_e32 v140, v7, v9
	v_add_u32_e32 v7, 0x2000, v7
	v_sub_u32_e32 v12, 0, v8
	v_max_i32_e32 v12, v8, v12
	v_mul_hi_u32 v13, v12, v6
	v_mul_lo_u32 v14, v13, s29
	v_sub_u32_e32 v12, v12, v14
	v_add_u32_e32 v15, 1, v13
	v_cmp_le_u32_e32 vcc, s29, v12
	v_subrev_u32_e32 v14, s29, v12
	v_ashrrev_i32_e32 v9, 31, v8
	v_cndmask_b32_e32 v13, v13, v15, vcc
	v_cndmask_b32_e32 v12, v12, v14, vcc
	v_add_u32_e32 v14, 1, v13
	v_cmp_le_u32_e32 vcc, s29, v12
	v_mov_b64_e32 v[10:11], s[24:25]
	v_add_u32_e32 v8, 0x200, v8
	v_cndmask_b32_e32 v12, v13, v14, vcc
	v_xor_b32_e32 v14, v12, v9
	v_sub_u32_e32 v12, v14, v9
	v_add_u32_e32 v15, s63, v12
	v_mad_u64_u32 v[12:13], s[54:55], s53, v12, v[4:5]
	v_mad_i64_i32 v[10:11], s[54:55], v15, s64, v[10:11]
	v_ashrrev_i32_e32 v13, 31, v12
	v_lshl_add_u64 v[10:11], v[12:13], 1, v[10:11]
	global_load_dwordx4 v[120:123], v[10:11], off
	v_lshlrev_b32_e32 v9, 4, v9
	v_lshlrev_b32_e32 v14, 4, v14
	v_sub_u32_e32 v9, v14, v9
	v_add_u32_e32 v4, 0x1000, v4
	v_add_u32_e32 v141, v7, v9
	v_add_u32_e32 v7, 0x2000, v7
	v_sub_u32_e32 v12, 0, v8
	v_max_i32_e32 v12, v8, v12
	v_mul_hi_u32 v13, v12, v6
	v_mul_lo_u32 v14, v13, s29
	v_sub_u32_e32 v12, v12, v14
	v_add_u32_e32 v15, 1, v13
	v_cmp_le_u32_e32 vcc, s29, v12
	v_subrev_u32_e32 v14, s29, v12
	v_ashrrev_i32_e32 v9, 31, v8
	v_cndmask_b32_e32 v13, v13, v15, vcc
	v_cndmask_b32_e32 v12, v12, v14, vcc
	v_add_u32_e32 v14, 1, v13
	v_cmp_le_u32_e32 vcc, s29, v12
	v_mov_b64_e32 v[10:11], s[24:25]
	v_add_u32_e32 v8, 0x200, v8
	v_cndmask_b32_e32 v12, v13, v14, vcc
	v_xor_b32_e32 v14, v12, v9
	v_sub_u32_e32 v12, v14, v9
	v_add_u32_e32 v15, s63, v12
	v_mad_u64_u32 v[12:13], s[54:55], s53, v12, v[4:5]
	v_mad_i64_i32 v[10:11], s[54:55], v15, s64, v[10:11]
	v_ashrrev_i32_e32 v13, 31, v12
	v_lshl_add_u64 v[10:11], v[12:13], 1, v[10:11]
	global_load_dwordx4 v[124:127], v[10:11], off
	v_lshlrev_b32_e32 v9, 4, v9
	v_lshlrev_b32_e32 v14, 4, v14
	v_sub_u32_e32 v9, v14, v9
	v_add_u32_e32 v4, 0x1000, v4
	v_add_u32_e32 v142, v7, v9
	v_add_u32_e32 v7, 0x2000, v7
	v_sub_u32_e32 v12, 0, v8
	v_max_i32_e32 v12, v8, v12
	v_mul_hi_u32 v13, v12, v6
	v_mul_lo_u32 v14, v13, s29
	v_sub_u32_e32 v12, v12, v14
	v_add_u32_e32 v15, 1, v13
	v_cmp_le_u32_e32 vcc, s29, v12
	v_subrev_u32_e32 v14, s29, v12
	v_ashrrev_i32_e32 v9, 31, v8
	v_cndmask_b32_e32 v13, v13, v15, vcc
	v_cndmask_b32_e32 v12, v12, v14, vcc
	v_add_u32_e32 v14, 1, v13
	v_cmp_le_u32_e32 vcc, s29, v12
	v_mov_b64_e32 v[10:11], s[24:25]
	v_add_u32_e32 v8, 0x200, v8
	v_cndmask_b32_e32 v12, v13, v14, vcc
	v_xor_b32_e32 v14, v12, v9
	v_sub_u32_e32 v12, v14, v9
	v_add_u32_e32 v15, s63, v12
	v_mad_u64_u32 v[12:13], s[54:55], s53, v12, v[4:5]
	v_mad_i64_i32 v[10:11], s[54:55], v15, s64, v[10:11]
	v_ashrrev_i32_e32 v13, 31, v12
	v_lshl_add_u64 v[10:11], v[12:13], 1, v[10:11]
	global_load_dwordx4 v[128:131], v[10:11], off
	v_lshlrev_b32_e32 v9, 4, v9
	v_lshlrev_b32_e32 v14, 4, v14
	v_sub_u32_e32 v9, v14, v9
	v_add_u32_e32 v4, 0x1000, v4
	v_add_u32_e32 v143, v7, v9
	v_add_u32_e32 v7, 0x2000, v7
	s_cmp_lt_u32 s29, 24
	s_cbranch_scc1 .Lal_w4
	v_sub_u32_e32 v12, 0, v8
	v_max_i32_e32 v12, v8, v12
	v_mul_hi_u32 v13, v12, v6
	v_mul_lo_u32 v14, v13, s29
	v_sub_u32_e32 v12, v12, v14
	v_add_u32_e32 v15, 1, v13
	v_cmp_le_u32_e32 vcc, s29, v12
	v_subrev_u32_e32 v14, s29, v12
	v_ashrrev_i32_e32 v9, 31, v8
	v_cndmask_b32_e32 v13, v13, v15, vcc
	v_cndmask_b32_e32 v12, v12, v14, vcc
	v_add_u32_e32 v14, 1, v13
	v_cmp_le_u32_e32 vcc, s29, v12
	v_mov_b64_e32 v[10:11], s[24:25]
	v_add_u32_e32 v8, 0x200, v8
	v_cndmask_b32_e32 v12, v13, v14, vcc
	v_xor_b32_e32 v14, v12, v9
	v_sub_u32_e32 v12, v14, v9
	v_add_u32_e32 v15, s63, v12
	v_mad_u64_u32 v[12:13], s[54:55], s53, v12, v[4:5]
	v_mad_i64_i32 v[10:11], s[54:55], v15, s64, v[10:11]
	v_ashrrev_i32_e32 v13, 31, v12
	v_lshl_add_u64 v[10:11], v[12:13], 1, v[10:11]
	global_load_dwordx4 v[132:135], v[10:11], off
	v_lshlrev_b32_e32 v9, 4, v9
	v_lshlrev_b32_e32 v14, 4, v14
	v_sub_u32_e32 v9, v14, v9
	v_add_u32_e32 v4, 0x1000, v4
	v_add_u32_e32 v144, v7, v9
	v_add_u32_e32 v7, 0x2000, v7
	v_sub_u32_e32 v12, 0, v8
	v_max_i32_e32 v12, v8, v12
	v_mul_hi_u32 v13, v12, v6
	v_mul_lo_u32 v14, v13, s29
	v_sub_u32_e32 v12, v12, v14
	v_add_u32_e32 v15, 1, v13
	v_cmp_le_u32_e32 vcc, s29, v12
	v_subrev_u32_e32 v14, s29, v12
	v_ashrrev_i32_e32 v9, 31, v8
	v_cndmask_b32_e32 v13, v13, v15, vcc
	v_cndmask_b32_e32 v12, v12, v14, vcc
	v_add_u32_e32 v14, 1, v13
	v_cmp_le_u32_e32 vcc, s29, v12
	v_mov_b64_e32 v[10:11], s[24:25]
	v_add_u32_e32 v8, 0x200, v8
	v_cndmask_b32_e32 v12, v13, v14, vcc
	v_xor_b32_e32 v14, v12, v9
	v_sub_u32_e32 v12, v14, v9
	v_add_u32_e32 v15, s63, v12
	v_mad_u64_u32 v[12:13], s[54:55], s53, v12, v[4:5]
	v_mad_i64_i32 v[10:11], s[54:55], v15, s64, v[10:11]
	v_ashrrev_i32_e32 v13, 31, v12
	v_lshl_add_u64 v[10:11], v[12:13], 1, v[10:11]
	global_load_dwordx4 v[136:139], v[10:11], off
	v_lshlrev_b32_e32 v9, 4, v9
	v_lshlrev_b32_e32 v14, 4, v14
	v_sub_u32_e32 v9, v14, v9
	v_add_u32_e32 v4, 0x1000, v4
	v_add_u32_e32 v145, v7, v9
	v_add_u32_e32 v7, 0x2000, v7
	s_waitcnt vmcnt(5)
	ds_write_b128 v140, v[116:119]
	s_waitcnt vmcnt(4)
	ds_write_b128 v141, v[120:123]
	s_waitcnt vmcnt(3)
	ds_write_b128 v142, v[124:127]
	s_waitcnt vmcnt(2)
	ds_write_b128 v143, v[128:131]
	s_waitcnt vmcnt(1)
	ds_write_b128 v144, v[132:135]
	s_waitcnt vmcnt(0)
	ds_write_b128 v145, v[136:139]
	s_branch .Lal_done
; DI float bf2f(u16 b) { return __uint_as_float(((unsigned)b) << 16); }
; DI void phase_mla_up(const Params& p, int layer, char* lds) {
;     ...
;       for (int c = tid; c < 128 * CPR; c += NTHR) { int row = c / CPR, ch = c % CPR;
;         *(u32x4*)(As + row * STR + ch * 16) = *(const u32x4*)(H + (size_t)(m0 + row) * DIN + acol + ch * 8); }
;       __syncthreads();
;       {
;         int row = tid >> 2, part4 = tid & 3, n = K / 4; float ss = 0.f;
;         const u16* ar = (const u16*)(As + row * STR) + part4 * n;
;         for (int i = 0; i < n; ++i) { float v = bf2f(ar[i]); ss += v * v; }
;         ss += __shfl_xor(ss, 1); ss += __shfl_xor(ss, 2);
;         if (part4 == 0) rinv[row] = rsqrtf(ss / (float)K + 1e-6f);
.Lal_w4:
	s_waitcnt vmcnt(3)
	ds_write_b128 v140, v[116:119]
	s_waitcnt vmcnt(2)
	ds_write_b128 v141, v[120:123]
	s_waitcnt vmcnt(1)
	ds_write_b128 v142, v[124:127]
	s_waitcnt vmcnt(0)
	ds_write_b128 v143, v[128:131]
.Lal_done:
.LBB0_172:
	s_or_b64 exec, exec, s[20:21]
	s_lshl_b32 s24, s49, 1
	s_or_b32 s76, s24, 16
	s_lshr_b32 s24, s49, 2
	v_mul_u32_u24_e32 v6, s24, v82
	v_mul_lo_u32 v4, s76, v73
	v_lshlrev_b32_e32 v6, 1, v6
	s_xor_b64 s[20:21], s[12:13], -1
	v_add3_u32 v6, 0, v4, v6
	v_mov_b32_e32 v4, 0
	s_waitcnt lgkmcnt(0)
	s_barrier
.LBB0_173:
	ds_read_b128 v[116:119], v6
	ds_read_b128 v[120:123], v6 offset:16
	ds_read_b128 v[124:127], v6 offset:32
	ds_read_b128 v[128:131], v6 offset:48
	s_cmp_lt_u32 s24, 48
	s_cbranch_scc1 .Lrinv_rd4
	ds_read_b128 v[132:135], v6 offset:64
	ds_read_b128 v[136:139], v6 offset:80
.Lrinv_rd4:
	s_waitcnt lgkmcnt(0)
	v_lshlrev_b32_e32 v7, 16, v116
	v_fmac_f32_e32 v4, v7, v7
	v_and_b32_e32 v7, 0xffff0000, v116
	v_fmac_f32_e32 v4, v7, v7
	v_lshlrev_b32_e32 v7, 16, v117
	v_fmac_f32_e32 v4, v7, v7
	v_and_b32_e32 v7, 0xffff0000, v117
	v_fmac_f32_e32 v4, v7, v7
	v_lshlrev_b32_e32 v7, 16, v118
	v_fmac_f32_e32 v4, v7, v7
	v_and_b32_e32 v7, 0xffff0000, v118
	v_fmac_f32_e32 v4, v7, v7
	v_lshlrev_b32_e32 v7, 16, v119
	v_fmac_f32_e32 v4, v7, v7
	v_and_b32_e32 v7, 0xffff0000, v119
	v_fmac_f32_e32 v4, v7, v7
	v_lshlrev_b32_e32 v7, 16, v120
	v_fmac_f32_e32 v4, v7, v7
	v_and_b32_e32 v7, 0xffff0000, v120
	v_fmac_f32_e32 v4, v7, v7
	v_lshlrev_b32_e32 v7, 16, v121
	v_fmac_f32_e32 v4, v7, v7
	v_and_b32_e32 v7, 0xffff0000, v121
	v_fmac_f32_e32 v4, v7, v7
	v_lshlrev_b32_e32 v7, 16, v122
	v_fmac_f32_e32 v4, v7, v7
	v_and_b32_e32 v7, 0xffff0000, v122
	v_fmac_f32_e32 v4, v7, v7
	v_lshlrev_b32_e32 v7, 16, v123
	v_fmac_f32_e32 v4, v7, v7
	v_and_b32_e32 v7, 0xffff0000, v123
	v_fmac_f32_e32 v4, v7, v7
	v_lshlrev_b32_e32 v7, 16, v124
	v_fmac_f32_e32 v4, v7, v7
	v_and_b32_e32 v7, 0xffff0000, v124
	v_fmac_f32_e32 v4, v7, v7
	v_lshlrev_b32_e32 v7, 16, v125
	v_fmac_f32_e32 v4, v7, v7
	v_and_b32_e32 v7, 0xffff0000, v125
	v_fmac_f32_e32 v4, v7, v7
	v_lshlrev_b32_e32 v7, 16, v126
	v_fmac_f32_e32 v4, v7, v7
	v_and_b32_e32 v7, 0xffff0000, v126
	v_fmac_f32_e32 v4, v7, v7
	v_lshlrev_b32_e32 v7, 16, v127
	v_fmac_f32_e32 v4, v7, v7
	v_and_b32_e32 v7, 0xffff0000, v127
	v_fmac_f32_e32 v4, v7, v7
	v_lshlrev_b32_e32 v7, 16, v128
	v_fmac_f32_e32 v4, v7, v7
	v_and_b32_e32 v7, 0xffff0000, v128
	v_fmac_f32_e32 v4, v7, v7
	v_lshlrev_b32_e32 v7, 16, v129
	v_fmac_f32_e32 v4, v7, v7
	v_and_b32_e32 v7, 0xffff0000, v129
	v_fmac_f32_e32 v4, v7, v7
	v_lshlrev_b32_e32 v7, 16, v130
	v_fmac_f32_e32 v4, v7, v7
	v_and_b32_e32 v7, 0xffff0000, v130
	v_fmac_f32_e32 v4, v7, v7
	v_lshlrev_b32_e32 v7, 16, v131
	v_fmac_f32_e32 v4, v7, v7
	v_and_b32_e32 v7, 0xffff0000, v131
	v_fmac_f32_e32 v4, v7, v7
	s_cmp_lt_u32 s24, 48
	s_cbranch_scc1 .Lrinv_done
	v_lshlrev_b32_e32 v7, 16, v132
	v_fmac_f32_e32 v4, v7, v7
	v_and_b32_e32 v7, 0xffff0000, v132
	v_fmac_f32_e32 v4, v7, v7
	v_lshlrev_b32_e32 v7, 16, v133
	v_fmac_f32_e32 v4, v7, v7
	v_and_b32_e32 v7, 0xffff0000, v133
	v_fmac_f32_e32 v4, v7, v7
	v_lshlrev_b32_e32 v7, 16, v134
	v_fmac_f32_e32 v4, v7, v7
	v_and_b32_e32 v7, 0xffff0000, v134
	v_fmac_f32_e32 v4, v7, v7
	v_lshlrev_b32_e32 v7, 16, v135
	v_fmac_f32_e32 v4, v7, v7
	v_and_b32_e32 v7, 0xffff0000, v135
	v_fmac_f32_e32 v4, v7, v7
	v_lshlrev_b32_e32 v7, 16, v136
	v_fmac_f32_e32 v4, v7, v7
	v_and_b32_e32 v7, 0xffff0000, v136
	v_fmac_f32_e32 v4, v7, v7
	v_lshlrev_b32_e32 v7, 16, v137
	v_fmac_f32_e32 v4, v7, v7
	v_and_b32_e32 v7, 0xffff0000, v137
	v_fmac_f32_e32 v4, v7, v7
	v_lshlrev_b32_e32 v7, 16, v138
	v_fmac_f32_e32 v4, v7, v7
	v_and_b32_e32 v7, 0xffff0000, v138
	v_fmac_f32_e32 v4, v7, v7
	v_lshlrev_b32_e32 v7, 16, v139
	v_fmac_f32_e32 v4, v7, v7
	v_and_b32_e32 v7, 0xffff0000, v139
	v_fmac_f32_e32 v4, v7, v7
.Lrinv_done:
	ds_bpermute_b32 v6, v83, v4
	s_waitcnt lgkmcnt(0)
	v_add_f32_e32 v4, v4, v6
	ds_bpermute_b32 v6, v84, v4
	s_and_saveexec_b64 s[24:25], s[4:5]
	s_cbranch_execz .LBB0_176
	s_waitcnt lgkmcnt(0)
	v_add_f32_e32 v4, v4, v6
	v_cvt_f32_ubyte0_e32 v6, s49
	v_div_scale_f32 v7, s[26:27], v6, v6, v4
	v_rcp_f32_e32 v8, v7
	s_nop 0
	v_fma_f32 v9, -v7, v8, 1.0
	v_fmac_f32_e32 v8, v9, v8
	v_div_scale_f32 v9, vcc, v4, v6, v4
	v_mul_f32_e32 v10, v9, v8
	v_fma_f32 v11, -v7, v10, v9
	v_fmac_f32_e32 v10, v11, v8
	v_fma_f32 v7, -v7, v10, v9
	v_div_fmas_f32 v7, v7, v8, v10
	v_div_fixup_f32 v4, v7, v6, v4
	v_add_f32_e32 v4, 0x358637bd, v4
	v_mul_f32_e32 v6, 0x4b800000, v4
	v_cmp_gt_f32_e32 vcc, s65, v4
	s_nop 1
	v_cndmask_b32_e32 v4, v4, v6, vcc
	v_rsq_f32_e32 v4, v4
	s_nop 0
	v_mul_f32_e32 v6, 0x45800000, v4
	v_cndmask_b32_e32 v4, v4, v6, vcc
	ds_write_b32 v87, v4

; DI u16 f2bf(float x) { unsigned u = __float_as_uint(x); u += 0x7fffu + ((u >> 16) & 1u); return (u16)(u >> 16); }
; DI float bf2f(u16 b) { return __uint_as_float(((unsigned)b) << 16); }
; DI void phase_mla_up(const Params& p, int layer, char* lds) {
;     ...
;     for (int idx = tid; idx < 128 * 16; idx += NTHR) {
;       const int row = idx >> 4, i = idx & 15, trow = m0 + row;
;       float x1 = bf2f(H[(size_t)trow * DIN + C_KR + i]), x2 = bf2f(H[(size_t)trow * DIN + C_KR + 16 + i]);
;       f32x2 cs = rt[(size_t)(trow & (S - 1)) * 16 + i];
;       u16 o1 = f2bf(x1 * cs[0] - x2 * cs[1]), o2 = f2bf(x2 * cs[0] + x1 * cs[1]);
; #pragma unroll
;       for (int hd = 0; hd < 6; ++hd) { const size_t hrow = (size_t)((trow >> 13) * 6 + hd) * S + (trow & (S - 1)); KB[hrow * 96 + 64 + i] = o1; KB[hrow * 96 + 80 + i] = o2; }
;     }
.LBB0_304:
	v_ashrrev_i32_e32 v4, 4, v59
	v_add_u32_e32 v144, s63, v4
	v_add_u32_e32 v140, 0, v144
	v_mad_i64_i32 v[8:9], s[24:25], v140, s64, v[68:69]
	global_load_ushort v116, v[8:9], off offset:640
	global_load_ushort v117, v[8:9], off offset:672
	v_and_b32_e32 v4, 0x1fff, v140
	v_lshlrev_b32_e32 v4, 7, v4
	v_lshl_add_u64 v[8:9], v[64:65], 0, v[4:5]
	global_load_dwordx2 v[118:119], v[8:9], off
	v_add_u32_e32 v141, 32, v144
	v_mad_i64_i32 v[8:9], s[24:25], v141, s64, v[68:69]
	global_load_ushort v120, v[8:9], off offset:640
	global_load_ushort v121, v[8:9], off offset:672
	v_and_b32_e32 v4, 0x1fff, v141
	v_lshlrev_b32_e32 v4, 7, v4
	v_lshl_add_u64 v[8:9], v[64:65], 0, v[4:5]
	global_load_dwordx2 v[122:123], v[8:9], off
	v_add_u32_e32 v142, 64, v144
	v_mad_i64_i32 v[8:9], s[24:25], v142, s64, v[68:69]
	global_load_ushort v124, v[8:9], off offset:640
	global_load_ushort v125, v[8:9], off offset:672
	v_and_b32_e32 v4, 0x1fff, v142
	v_lshlrev_b32_e32 v4, 7, v4
	v_lshl_add_u64 v[8:9], v[64:65], 0, v[4:5]
	global_load_dwordx2 v[126:127], v[8:9], off
	v_add_u32_e32 v143, 96, v144
	v_mad_i64_i32 v[8:9], s[24:25], v143, s64, v[68:69]
	global_load_ushort v128, v[8:9], off offset:640
	global_load_ushort v129, v[8:9], off offset:672
	v_and_b32_e32 v4, 0x1fff, v143
	v_lshlrev_b32_e32 v4, 7, v4
	v_lshl_add_u64 v[8:9], v[64:65], 0, v[4:5]
	global_load_dwordx2 v[130:131], v[8:9], off
	s_waitcnt vmcnt(0)
	v_and_b32_e32 v14, 0x1fff, v140
	v_ashrrev_i32_e32 v7, 13, v140
	v_lshlrev_b32_e32 v10, 16, v116
	v_lshlrev_b32_e32 v11, 16, v117
	v_mov_b32_e32 v8, v118
	v_mov_b32_e32 v9, v119
	v_mul_f32_e32 v4, v9, v11
	v_fma_f32 v4, v8, v10, -v4
	v_mul_f32_e32 v8, v8, v11
	v_fmac_f32_e32 v8, v9, v10
	v_bfe_u32 v9, v8, 16, 1
	v_add3_u32 v8, v8, v9, s45
	v_lshrrev_b32_e32 v15, 16, v8
	v_mul_i32_i24_e32 v8, 6, v7
	v_ashrrev_i32_e32 v9, 31, v8
	v_lshlrev_b64 v[10:11], 13, v[8:9]
	v_or_b32_e32 v8, 1, v8
	v_bfe_u32 v12, v4, 16, 1
	v_or_b32_e32 v10, v10, v14
	v_ashrrev_i32_e32 v9, 31, v8
	v_add3_u32 v4, v4, v12, s45
	v_mad_u64_u32 v[12:13], s[24:25], v10, s33, v[70:71]
	v_lshlrev_b64 v[8:9], 13, v[8:9]
	v_lshrrev_b32_e32 v4, 16, v4
	v_mad_i32_i24 v13, v11, s33, v13
	v_or_b32_e32 v7, v8, v14
	global_store_short v[12:13], v4, off offset:128
	global_store_short v[12:13], v15, off offset:160
	v_mad_u64_u32 v[12:13], s[24:25], v7, s33, v[70:71]
	s_mov_b64 s[24:25], 0x4000
	v_mad_i32_i24 v13, v9, s33, v13
	v_lshl_add_u64 v[8:9], v[10:11], 0, s[24:25]
	global_store_short v[12:13], v4, off offset:128
	global_store_short v[12:13], v15, off offset:160
	v_mad_u64_u32 v[12:13], s[24:25], v8, s33, v[70:71]
	s_mov_b64 s[24:25], 0x6000
	v_mad_i32_i24 v13, v9, s33, v13
	v_lshl_add_u64 v[8:9], v[10:11], 0, s[24:25]
	global_store_short v[12:13], v4, off offset:128
	global_store_short v[12:13], v15, off offset:160
	v_mad_u64_u32 v[12:13], s[24:25], v8, s33, v[70:71]
	v_mad_i32_i24 v13, v9, s33, v13
	v_lshl_add_u64 v[8:9], v[10:11], 0, s[26:27]
	global_store_short v[12:13], v4, off offset:128
	global_store_short v[12:13], v15, off offset:160
	v_mad_u64_u32 v[12:13], s[24:25], v8, s33, v[70:71]
	s_mov_b64 s[24:25], 0xa000
	v_mad_i32_i24 v13, v9, s33, v13
	v_lshl_add_u64 v[8:9], v[10:11], 0, s[24:25]
	v_mad_u64_u32 v[10:11], s[24:25], v8, s33, v[70:71]
	v_mad_i32_i24 v11, v9, s33, v11
	s_movk_i32 s24, 0x5ff
	global_store_short v[12:13], v4, off offset:128
	global_store_short v[12:13], v15, off offset:160
	global_store_short v[10:11], v4, off offset:128
	global_store_short v[10:11], v15, off offset:160
	v_and_b32_e32 v14, 0x1fff, v141
	v_ashrrev_i32_e32 v7, 13, v141
	v_lshlrev_b32_e32 v10, 16, v120
	v_lshlrev_b32_e32 v11, 16, v121
	v_mov_b32_e32 v8, v122
	v_mov_b32_e32 v9, v123
	v_mul_f32_e32 v4, v9, v11
	v_fma_f32 v4, v8, v10, -v4
	v_mul_f32_e32 v8, v8, v11
	v_fmac_f32_e32 v8, v9, v10
	v_bfe_u32 v9, v8, 16, 1
	v_add3_u32 v8, v8, v9, s45
	v_lshrrev_b32_e32 v15, 16, v8
	v_mul_i32_i24_e32 v8, 6, v7
	v_ashrrev_i32_e32 v9, 31, v8
	v_lshlrev_b64 v[10:11], 13, v[8:9]
	v_or_b32_e32 v8, 1, v8
	v_bfe_u32 v12, v4, 16, 1
	v_or_b32_e32 v10, v10, v14
	v_ashrrev_i32_e32 v9, 31, v8
	v_add3_u32 v4, v4, v12, s45
	v_mad_u64_u32 v[12:13], s[24:25], v10, s33, v[70:71]
	v_lshlrev_b64 v[8:9], 13, v[8:9]
	v_lshrrev_b32_e32 v4, 16, v4
	v_mad_i32_i24 v13, v11, s33, v13
	v_or_b32_e32 v7, v8, v14
	global_store_short v[12:13], v4, off offset:128
	global_store_short v[12:13], v15, off offset:160
	v_mad_u64_u32 v[12:13], s[24:25], v7, s33, v[70:71]
	s_mov_b64 s[24:25], 0x4000
	v_mad_i32_i24 v13, v9, s33, v13
	v_lshl_add_u64 v[8:9], v[10:11], 0, s[24:25]
	global_store_short v[12:13], v4, off offset:128
	global_store_short v[12:13], v15, off offset:160
	v_mad_u64_u32 v[12:13], s[24:25], v8, s33, v[70:71]
	s_mov_b64 s[24:25], 0x6000
	v_mad_i32_i24 v13, v9, s33, v13
	v_lshl_add_u64 v[8:9], v[10:11], 0, s[24:25]
	global_store_short v[12:13], v4, off offset:128
	global_store_short v[12:13], v15, off offset:160
; DI u16 f2bf(float x) { unsigned u = __float_as_uint(x); u += 0x7fffu + ((u >> 16) & 1u); return (u16)(u >> 16); }
; DI float bf2f(u16 b) { return __uint_as_float(((unsigned)b) << 16); }
; DI void phase_mla_up(const Params& p, int layer, char* lds) {
;     ...
;     for (int idx = tid; idx < 128 * 16; idx += NTHR) {
;       const int row = idx >> 4, i = idx & 15, trow = m0 + row;
;       float x1 = bf2f(H[(size_t)trow * DIN + C_KR + i]), x2 = bf2f(H[(size_t)trow * DIN + C_KR + 16 + i]);
;       f32x2 cs = rt[(size_t)(trow & (S - 1)) * 16 + i];
;       u16 o1 = f2bf(x1 * cs[0] - x2 * cs[1]), o2 = f2bf(x2 * cs[0] + x1 * cs[1]);
; #pragma unroll
;       for (int hd = 0; hd < 6; ++hd) { const size_t hrow = (size_t)((trow >> 13) * 6 + hd) * S + (trow & (S - 1)); KB[hrow * 96 + 64 + i] = o1; KB[hrow * 96 + 80 + i] = o2; }
;     }
	v_mad_u64_u32 v[12:13], s[24:25], v8, s33, v[70:71]
	v_mad_i32_i24 v13, v9, s33, v13
	v_lshl_add_u64 v[8:9], v[10:11], 0, s[26:27]
	global_store_short v[12:13], v4, off offset:128
	global_store_short v[12:13], v15, off offset:160
	v_mad_u64_u32 v[12:13], s[24:25], v8, s33, v[70:71]
	s_mov_b64 s[24:25], 0xa000
	v_mad_i32_i24 v13, v9, s33, v13
	v_lshl_add_u64 v[8:9], v[10:11], 0, s[24:25]
	v_mad_u64_u32 v[10:11], s[24:25], v8, s33, v[70:71]
	v_mad_i32_i24 v11, v9, s33, v11
	s_movk_i32 s24, 0x5ff
	global_store_short v[12:13], v4, off offset:128
	global_store_short v[12:13], v15, off offset:160
	global_store_short v[10:11], v4, off offset:128
	global_store_short v[10:11], v15, off offset:160
	v_and_b32_e32 v14, 0x1fff, v142
	v_ashrrev_i32_e32 v7, 13, v142
	v_lshlrev_b32_e32 v10, 16, v124
	v_lshlrev_b32_e32 v11, 16, v125
	v_mov_b32_e32 v8, v126
	v_mov_b32_e32 v9, v127
	v_mul_f32_e32 v4, v9, v11
	v_fma_f32 v4, v8, v10, -v4
	v_mul_f32_e32 v8, v8, v11
	v_fmac_f32_e32 v8, v9, v10
	v_bfe_u32 v9, v8, 16, 1
	v_add3_u32 v8, v8, v9, s45
	v_lshrrev_b32_e32 v15, 16, v8
	v_mul_i32_i24_e32 v8, 6, v7
	v_ashrrev_i32_e32 v9, 31, v8
	v_lshlrev_b64 v[10:11], 13, v[8:9]
	v_or_b32_e32 v8, 1, v8
	v_bfe_u32 v12, v4, 16, 1
	v_or_b32_e32 v10, v10, v14
	v_ashrrev_i32_e32 v9, 31, v8
	v_add3_u32 v4, v4, v12, s45
	v_mad_u64_u32 v[12:13], s[24:25], v10, s33, v[70:71]
	v_lshlrev_b64 v[8:9], 13, v[8:9]
	v_lshrrev_b32_e32 v4, 16, v4
	v_mad_i32_i24 v13, v11, s33, v13
	v_or_b32_e32 v7, v8, v14
	global_store_short v[12:13], v4, off offset:128
	global_store_short v[12:13], v15, off offset:160
	v_mad_u64_u32 v[12:13], s[24:25], v7, s33, v[70:71]
	s_mov_b64 s[24:25], 0x4000
	v_mad_i32_i24 v13, v9, s33, v13
	v_lshl_add_u64 v[8:9], v[10:11], 0, s[24:25]
	global_store_short v[12:13], v4, off offset:128
	global_store_short v[12:13], v15, off offset:160
	v_mad_u64_u32 v[12:13], s[24:25], v8, s33, v[70:71]
	s_mov_b64 s[24:25], 0x6000
	v_mad_i32_i24 v13, v9, s33, v13
	v_lshl_add_u64 v[8:9], v[10:11], 0, s[24:25]
	global_store_short v[12:13], v4, off offset:128
	global_store_short v[12:13], v15, off offset:160
	v_mad_u64_u32 v[12:13], s[24:25], v8, s33, v[70:71]
	v_mad_i32_i24 v13, v9, s33, v13
	v_lshl_add_u64 v[8:9], v[10:11], 0, s[26:27]
	global_store_short v[12:13], v4, off offset:128
	global_store_short v[12:13], v15, off offset:160
	v_mad_u64_u32 v[12:13], s[24:25], v8, s33, v[70:71]
	s_mov_b64 s[24:25], 0xa000
	v_mad_i32_i24 v13, v9, s33, v13
	v_lshl_add_u64 v[8:9], v[10:11], 0, s[24:25]
	v_mad_u64_u32 v[10:11], s[24:25], v8, s33, v[70:71]
	v_mad_i32_i24 v11, v9, s33, v11
	s_movk_i32 s24, 0x5ff
	global_store_short v[12:13], v4, off offset:128
	global_store_short v[12:13], v15, off offset:160
	global_store_short v[10:11], v4, off offset:128
	global_store_short v[10:11], v15, off offset:160
	v_and_b32_e32 v14, 0x1fff, v143
	v_ashrrev_i32_e32 v7, 13, v143
	v_lshlrev_b32_e32 v10, 16, v128
	v_lshlrev_b32_e32 v11, 16, v129
	v_mov_b32_e32 v8, v130
	v_mov_b32_e32 v9, v131
	v_mul_f32_e32 v4, v9, v11
	v_fma_f32 v4, v8, v10, -v4
	v_mul_f32_e32 v8, v8, v11
	v_fmac_f32_e32 v8, v9, v10
	v_bfe_u32 v9, v8, 16, 1
	v_add3_u32 v8, v8, v9, s45
	v_lshrrev_b32_e32 v15, 16, v8
	v_mul_i32_i24_e32 v8, 6, v7
	v_ashrrev_i32_e32 v9, 31, v8
	v_lshlrev_b64 v[10:11], 13, v[8:9]
	v_or_b32_e32 v8, 1, v8
	v_bfe_u32 v12, v4, 16, 1
	v_or_b32_e32 v10, v10, v14
	v_ashrrev_i32_e32 v9, 31, v8
	v_add3_u32 v4, v4, v12, s45
	v_mad_u64_u32 v[12:13], s[24:25], v10, s33, v[70:71]
	v_lshlrev_b64 v[8:9], 13, v[8:9]
	v_lshrrev_b32_e32 v4, 16, v4
	v_mad_i32_i24 v13, v11, s33, v13
	v_or_b32_e32 v7, v8, v14
	global_store_short v[12:13], v4, off offset:128
	global_store_short v[12:13], v15, off offset:160
	v_mad_u64_u32 v[12:13], s[24:25], v7, s33, v[70:71]
	s_mov_b64 s[24:25], 0x4000
	v_mad_i32_i24 v13, v9, s33, v13
	v_lshl_add_u64 v[8:9], v[10:11], 0, s[24:25]
	global_store_short v[12:13], v4, off offset:128
	global_store_short v[12:13], v15, off offset:160
	v_mad_u64_u32 v[12:13], s[24:25], v8, s33, v[70:71]
	s_mov_b64 s[24:25], 0x6000
	v_mad_i32_i24 v13, v9, s33, v13
	v_lshl_add_u64 v[8:9], v[10:11], 0, s[24:25]
	global_store_short v[12:13], v4, off offset:128
	global_store_short v[12:13], v15, off offset:160
	v_mad_u64_u32 v[12:13], s[24:25], v8, s33, v[70:71]
	v_mad_i32_i24 v13, v9, s33, v13
	v_lshl_add_u64 v[8:9], v[10:11], 0, s[26:27]
	global_store_short v[12:13], v4, off offset:128
	global_store_short v[12:13], v15, off offset:160
	v_mad_u64_u32 v[12:13], s[24:25], v8, s33, v[70:71]
	s_mov_b64 s[24:25], 0xa000
	v_mad_i32_i24 v13, v9, s33, v13
	v_lshl_add_u64 v[8:9], v[10:11], 0, s[24:25]
	v_mad_u64_u32 v[10:11], s[24:25], v8, s33, v[70:71]
	v_mad_i32_i24 v11, v9, s33, v11
	s_movk_i32 s24, 0x5ff
	global_store_short v[12:13], v4, off offset:128
	global_store_short v[12:13], v15, off offset:160
	global_store_short v[10:11], v4, off offset:128
	global_store_short v[10:11], v15, off offset:160
	s_branch .LBB0_166
